# P6 epilogue rewritten by hand: quad lanes exchange packed bf16 via ds_bpermute so 4 adjacent lanes store 64 contiguous bytes (coalesced H stores)
# speedup vs baseline: 1.0091x; 1.0035x over previous
.LBB0_961:
	ds_read_b128 v[144:147], v155
	ds_read_b128 v[148:151], v155 offset:1024
	ds_read_b128 v[158:161], v155 offset:2048
	ds_read_b128 v[162:165], v155 offset:3072
	ds_read_b128 v[166:169], v156
	ds_read_b128 v[170:173], v156 offset:1024
	ds_read_b128 v[174:177], v156 offset:2048
	ds_read_b128 v[178:181], v156 offset:3072
	s_add_i32 s78, s10, 2
	s_add_u32 s33, s46, 0x80
	s_addc_u32 s11, s47, 0
	s_cmp_eq_u32 s65, s10
	s_cselect_b32 s10, s4, s33
	s_cselect_b32 s11, s5, s11
	s_cselect_b32 s81, s45, s49
	s_cselect_b32 s80, s44, s48
	v_lshl_add_u64 v[218:219], s[46:47], 0, v[136:137]
	s_add_i32 m0, s35, 0xc000
	ds_read_b128 v[182:185], v157
	ds_read_b128 v[186:189], v157 offset:1024
	ds_read_b128 v[190:193], v157 offset:2048
	ds_read_b128 v[194:197], v157 offset:3072
	ds_read_b128 v[198:201], v157 offset:4096
	ds_read_b128 v[204:207], v157 offset:5120
	ds_read_b128 v[210:213], v157 offset:6144
	ds_read_b128 v[214:217], v157 offset:7168
	global_load_lds_dwordx4 v[218:219], off
	v_lshl_add_u64 v[218:219], s[46:47], 0, v[138:139]
	s_add_i32 m0, s35, 0xe000
	s_nop 0
	global_load_lds_dwordx4 v[218:219], off
	s_waitcnt vmcnt(8)
	s_waitcnt lgkmcnt(0)
	s_barrier
	s_setprio 1
	s_waitcnt lgkmcnt(0)
	v_mfma_f32_16x16x32_bf16 v[124:127], v[144:147], v[182:185], v[124:127]
	v_mfma_f32_16x16x32_bf16 v[120:123], v[158:161], v[182:185], v[120:123]
	v_mfma_f32_16x16x32_bf16 v[116:119], v[144:147], v[190:193], v[116:119]
	v_mfma_f32_16x16x32_bf16 v[108:111], v[158:161], v[190:193], v[108:111]
	v_mfma_f32_16x16x32_bf16 v[100:103], v[144:147], v[198:201], v[100:103]
	v_mfma_f32_16x16x32_bf16 v[92:95], v[158:161], v[198:201], v[92:95]
	v_mfma_f32_16x16x32_bf16 v[84:87], v[144:147], v[210:213], v[84:87]
	v_mfma_f32_16x16x32_bf16 v[76:79], v[158:161], v[210:213], v[76:79]
	v_mfma_f32_16x16x32_bf16 v[124:127], v[148:151], v[186:189], v[124:127]
	v_mfma_f32_16x16x32_bf16 v[120:123], v[162:165], v[186:189], v[120:123]
	v_mfma_f32_16x16x32_bf16 v[116:119], v[148:151], v[194:197], v[116:119]
	v_mfma_f32_16x16x32_bf16 v[108:111], v[162:165], v[194:197], v[108:111]
	v_mfma_f32_16x16x32_bf16 v[100:103], v[148:151], v[204:207], v[100:103]
	v_mfma_f32_16x16x32_bf16 v[92:95], v[162:165], v[204:207], v[92:95]
	v_mfma_f32_16x16x32_bf16 v[84:87], v[148:151], v[214:217], v[84:87]
	v_mfma_f32_16x16x32_bf16 v[76:79], v[162:165], v[214:217], v[76:79]
	s_setprio 0
	s_setprio 1
	v_mfma_f32_16x16x32_bf16 v[112:115], v[166:169], v[182:185], v[112:115]
	v_mfma_f32_16x16x32_bf16 v[104:107], v[174:177], v[182:185], v[104:107]
	v_mfma_f32_16x16x32_bf16 v[96:99], v[166:169], v[190:193], v[96:99]
	v_mfma_f32_16x16x32_bf16 v[88:91], v[174:177], v[190:193], v[88:91]
	v_mfma_f32_16x16x32_bf16 v[80:83], v[166:169], v[198:201], v[80:83]
	v_mfma_f32_16x16x32_bf16 v[72:75], v[174:177], v[198:201], v[72:75]
	v_mfma_f32_16x16x32_bf16 v[68:71], v[166:169], v[210:213], v[68:71]
	v_mfma_f32_16x16x32_bf16 v[64:67], v[174:177], v[210:213], v[64:67]
	v_mfma_f32_16x16x32_bf16 v[112:115], v[170:173], v[186:189], v[112:115]
	v_mfma_f32_16x16x32_bf16 v[104:107], v[178:181], v[186:189], v[104:107]
	v_mfma_f32_16x16x32_bf16 v[96:99], v[170:173], v[194:197], v[96:99]
	v_mfma_f32_16x16x32_bf16 v[88:91], v[178:181], v[194:197], v[88:91]
	v_mfma_f32_16x16x32_bf16 v[80:83], v[170:173], v[204:207], v[80:83]
	v_mfma_f32_16x16x32_bf16 v[72:75], v[178:181], v[204:207], v[72:75]
	v_mfma_f32_16x16x32_bf16 v[68:71], v[170:173], v[214:217], v[68:71]
	v_mfma_f32_16x16x32_bf16 v[64:67], v[178:181], v[214:217], v[64:67]
	s_setprio 0
	s_barrier
	s_add_i32 s33, s68, s34
	v_lshl_add_u64 v[218:219], s[80:81], 0, v[130:131]
	s_mov_b32 m0, s33
	ds_read_b128 v[182:185], v157 offset:16384
	ds_read_b128 v[186:189], v157 offset:17408
	ds_read_b128 v[190:193], v157 offset:18432
	ds_read_b128 v[194:197], v157 offset:19456
	ds_read_b128 v[198:201], v157 offset:20480
	ds_read_b128 v[204:207], v157 offset:21504
	ds_read_b128 v[210:213], v157 offset:22528
	ds_read_b128 v[214:217], v157 offset:23552
	global_load_lds_dwordx4 v[218:219], off
	s_add_i32 m0, s33, 0x2000
	v_lshl_add_u64 v[220:221], s[80:81], 0, v[134:135]
	s_add_u32 s80, s80, s16
	s_addc_u32 s81, s81, s17
	s_add_i32 s33, s69, s34
	global_load_lds_dwordx4 v[220:221], off
	v_lshl_add_u64 v[222:223], s[80:81], 0, v[130:131]
	s_mov_b32 m0, s33
	v_lshl_add_u64 v[224:225], s[80:81], 0, v[134:135]
	global_load_lds_dwordx4 v[222:223], off
	s_add_i32 m0, s33, 0x2000
	v_lshl_add_u64 v[226:227], s[10:11], 0, v[128:129]
	global_load_lds_dwordx4 v[224:225], off
	s_mov_b32 m0, s35
	v_lshl_add_u64 v[228:229], s[10:11], 0, v[132:133]
	global_load_lds_dwordx4 v[226:227], off
	s_mov_b32 m0, s50
	s_nop 0
	global_load_lds_dwordx4 v[228:229], off
	s_waitcnt vmcnt(8)
	s_waitcnt lgkmcnt(0)
	s_barrier
	s_setprio 1
	s_waitcnt lgkmcnt(0)
	v_mfma_f32_16x16x32_bf16 v[60:63], v[144:147], v[182:185], v[60:63]
	v_mfma_f32_16x16x32_bf16 v[56:59], v[158:161], v[182:185], v[56:59]
	v_mfma_f32_16x16x32_bf16 v[52:55], v[144:147], v[190:193], v[52:55]
	v_mfma_f32_16x16x32_bf16 v[44:47], v[158:161], v[190:193], v[44:47]
	v_mfma_f32_16x16x32_bf16 v[36:39], v[144:147], v[198:201], v[36:39]
	v_mfma_f32_16x16x32_bf16 v[28:31], v[158:161], v[198:201], v[28:31]
	v_mfma_f32_16x16x32_bf16 v[20:23], v[144:147], v[210:213], v[20:23]
	v_mfma_f32_16x16x32_bf16 v[12:15], v[158:161], v[210:213], v[12:15]
	v_mfma_f32_16x16x32_bf16 v[60:63], v[148:151], v[186:189], v[60:63]
	v_mfma_f32_16x16x32_bf16 v[56:59], v[162:165], v[186:189], v[56:59]
	v_mfma_f32_16x16x32_bf16 v[52:55], v[148:151], v[194:197], v[52:55]
	v_mfma_f32_16x16x32_bf16 v[44:47], v[162:165], v[194:197], v[44:47]
	v_mfma_f32_16x16x32_bf16 v[36:39], v[148:151], v[204:207], v[36:39]
	v_mfma_f32_16x16x32_bf16 v[28:31], v[162:165], v[204:207], v[28:31]
	v_mfma_f32_16x16x32_bf16 v[20:23], v[148:151], v[214:217], v[20:23]
	v_mfma_f32_16x16x32_bf16 v[12:15], v[162:165], v[214:217], v[12:15]
	s_setprio 0
	s_setprio 1
	v_mfma_f32_16x16x32_bf16 v[48:51], v[166:169], v[182:185], v[48:51]
	v_mfma_f32_16x16x32_bf16 v[40:43], v[174:177], v[182:185], v[40:43]
	v_mfma_f32_16x16x32_bf16 v[32:35], v[166:169], v[190:193], v[32:35]
	v_mfma_f32_16x16x32_bf16 v[24:27], v[174:177], v[190:193], v[24:27]
	v_mfma_f32_16x16x32_bf16 v[16:19], v[166:169], v[198:201], v[16:19]
	v_mfma_f32_16x16x32_bf16 v[8:11], v[174:177], v[198:201], v[8:11]
	v_mfma_f32_16x16x32_bf16 v[4:7], v[166:169], v[210:213], v[4:7]
	v_mfma_f32_16x16x32_bf16 v[0:3], v[174:177], v[210:213], v[0:3]
	v_mfma_f32_16x16x32_bf16 v[48:51], v[170:173], v[186:189], v[48:51]
	v_mfma_f32_16x16x32_bf16 v[40:43], v[178:181], v[186:189], v[40:43]
	v_mfma_f32_16x16x32_bf16 v[32:35], v[170:173], v[194:197], v[32:35]
	v_mfma_f32_16x16x32_bf16 v[24:27], v[178:181], v[194:197], v[24:27]
	v_mfma_f32_16x16x32_bf16 v[16:19], v[170:173], v[204:207], v[16:19]
	v_mfma_f32_16x16x32_bf16 v[8:11], v[178:181], v[204:207], v[8:11]
	v_mfma_f32_16x16x32_bf16 v[4:7], v[170:173], v[214:217], v[4:7]
	v_mfma_f32_16x16x32_bf16 v[0:3], v[178:181], v[214:217], v[0:3]
	s_setprio 0
	s_barrier
	s_add_i32 s33, 0, 0x18000
	s_add_i32 s79, 0, 0x1c000
	v_add_u32_e32 v162, s33, v153
	v_add_u32_e32 v178, s79, v153
	ds_read_b128 v[144:147], v162
	ds_read_b128 v[148:151], v162 offset:1024
	ds_read_b128 v[158:161], v162 offset:2048
	ds_read_b128 v[162:165], v162 offset:3072
	ds_read_b128 v[166:169], v178
	ds_read_b128 v[170:173], v178 offset:1024
	ds_read_b128 v[174:177], v178 offset:2048
	ds_read_b128 v[178:181], v178 offset:3072
	s_add_u32 s10, s10, s16
	s_addc_u32 s11, s11, s17
	s_mov_b32 m0, s51
	v_lshl_add_u64 v[230:231], s[10:11], 0, v[128:129]
	ds_read_b128 v[182:185], v157 offset:32768
	ds_read_b128 v[186:189], v157 offset:33792
	ds_read_b128 v[190:193], v157 offset:34816
	ds_read_b128 v[194:197], v157 offset:35840
	ds_read_b128 v[198:201], v157 offset:36864
	ds_read_b128 v[204:207], v157 offset:37888
	ds_read_b128 v[210:213], v157 offset:38912
	ds_read_b128 v[214:217], v157 offset:39936
	global_load_lds_dwordx4 v[230:231], off
	v_lshl_add_u64 v[230:231], s[10:11], 0, v[132:133]
	s_mov_b32 m0, s52
	s_nop 0
	global_load_lds_dwordx4 v[230:231], off
	s_waitcnt vmcnt(8)
	s_waitcnt lgkmcnt(0)
	s_barrier
	s_setprio 1
	s_waitcnt lgkmcnt(0)
	v_mfma_f32_16x16x32_bf16 v[124:127], v[144:147], v[182:185], v[124:127]
	v_mfma_f32_16x16x32_bf16 v[120:123], v[158:161], v[182:185], v[120:123]
	v_mfma_f32_16x16x32_bf16 v[116:119], v[144:147], v[190:193], v[116:119]
	v_mfma_f32_16x16x32_bf16 v[108:111], v[158:161], v[190:193], v[108:111]
	v_mfma_f32_16x16x32_bf16 v[100:103], v[144:147], v[198:201], v[100:103]
	v_mfma_f32_16x16x32_bf16 v[92:95], v[158:161], v[198:201], v[92:95]
	v_mfma_f32_16x16x32_bf16 v[84:87], v[144:147], v[210:213], v[84:87]
	v_mfma_f32_16x16x32_bf16 v[76:79], v[158:161], v[210:213], v[76:79]
	v_mfma_f32_16x16x32_bf16 v[124:127], v[148:151], v[186:189], v[124:127]
	v_mfma_f32_16x16x32_bf16 v[120:123], v[162:165], v[186:189], v[120:123]
	v_mfma_f32_16x16x32_bf16 v[116:119], v[148:151], v[194:197], v[116:119]
	v_mfma_f32_16x16x32_bf16 v[108:111], v[162:165], v[194:197], v[108:111]
	v_mfma_f32_16x16x32_bf16 v[100:103], v[148:151], v[204:207], v[100:103]
	v_mfma_f32_16x16x32_bf16 v[92:95], v[162:165], v[204:207], v[92:95]
	v_mfma_f32_16x16x32_bf16 v[84:87], v[148:151], v[214:217], v[84:87]
	v_mfma_f32_16x16x32_bf16 v[76:79], v[162:165], v[214:217], v[76:79]
	s_setprio 0
	s_setprio 1
	v_mfma_f32_16x16x32_bf16 v[112:115], v[166:169], v[182:185], v[112:115]
	v_mfma_f32_16x16x32_bf16 v[104:107], v[174:177], v[182:185], v[104:107]
	v_mfma_f32_16x16x32_bf16 v[96:99], v[166:169], v[190:193], v[96:99]
	v_mfma_f32_16x16x32_bf16 v[88:91], v[174:177], v[190:193], v[88:91]
	v_mfma_f32_16x16x32_bf16 v[80:83], v[166:169], v[198:201], v[80:83]
	v_mfma_f32_16x16x32_bf16 v[72:75], v[174:177], v[198:201], v[72:75]
	v_mfma_f32_16x16x32_bf16 v[68:71], v[166:169], v[210:213], v[68:71]
	v_mfma_f32_16x16x32_bf16 v[64:67], v[174:177], v[210:213], v[64:67]
	v_mfma_f32_16x16x32_bf16 v[112:115], v[170:173], v[186:189], v[112:115]
	v_mfma_f32_16x16x32_bf16 v[104:107], v[178:181], v[186:189], v[104:107]
	v_mfma_f32_16x16x32_bf16 v[96:99], v[170:173], v[194:197], v[96:99]
	v_mfma_f32_16x16x32_bf16 v[88:91], v[178:181], v[194:197], v[88:91]
	v_mfma_f32_16x16x32_bf16 v[80:83], v[170:173], v[204:207], v[80:83]
	v_mfma_f32_16x16x32_bf16 v[72:75], v[178:181], v[204:207], v[72:75]
	v_mfma_f32_16x16x32_bf16 v[68:71], v[170:173], v[214:217], v[68:71]
	v_mfma_f32_16x16x32_bf16 v[64:67], v[178:181], v[214:217], v[64:67]
	s_setprio 0
	s_barrier
	s_add_i32 s10, s33, s34
	v_lshl_add_u64 v[218:219], v[218:219], 0, s[22:23]
	s_mov_b32 m0, s10
	ds_read_b128 v[182:185], v157 offset:49152
	ds_read_b128 v[186:189], v157 offset:50176
	ds_read_b128 v[190:193], v157 offset:51200
	ds_read_b128 v[194:197], v157 offset:52224
	ds_read_b128 v[198:201], v157 offset:53248
	ds_read_b128 v[204:207], v157 offset:54272
	ds_read_b128 v[210:213], v157 offset:55296
	ds_read_b128 v[214:217], v157 offset:56320
	global_load_lds_dwordx4 v[218:219], off
	v_lshl_add_u64 v[218:219], v[220:221], 0, s[22:23]
	s_add_i32 m0, s10, 0x2000
	s_add_i32 s10, s79, s34
	global_load_lds_dwordx4 v[218:219], off
	v_lshl_add_u64 v[218:219], v[222:223], 0, s[22:23]
	s_mov_b32 m0, s10
	s_nop 0
	global_load_lds_dwordx4 v[218:219], off
	v_lshl_add_u64 v[218:219], v[224:225], 0, s[22:23]
	s_add_i32 m0, s10, 0x2000
	s_nop 0
	global_load_lds_dwordx4 v[218:219], off
	v_lshl_add_u64 v[218:219], v[226:227], 0, s[22:23]
	s_mov_b32 m0, s62
	s_nop 0
	global_load_lds_dwordx4 v[218:219], off
	v_lshl_add_u64 v[218:219], v[228:229], 0, s[22:23]
	s_mov_b32 m0, s63
	s_nop 0
	global_load_lds_dwordx4 v[218:219], off
	s_waitcnt vmcnt(8)
	s_waitcnt lgkmcnt(0)
	s_barrier
	s_setprio 1
	s_waitcnt lgkmcnt(0)
	v_mfma_f32_16x16x32_bf16 v[60:63], v[144:147], v[182:185], v[60:63]
	v_mfma_f32_16x16x32_bf16 v[56:59], v[158:161], v[182:185], v[56:59]
	v_mfma_f32_16x16x32_bf16 v[52:55], v[144:147], v[190:193], v[52:55]
	v_mfma_f32_16x16x32_bf16 v[44:47], v[158:161], v[190:193], v[44:47]
	v_mfma_f32_16x16x32_bf16 v[36:39], v[144:147], v[198:201], v[36:39]
	v_mfma_f32_16x16x32_bf16 v[28:31], v[158:161], v[198:201], v[28:31]
	v_mfma_f32_16x16x32_bf16 v[20:23], v[144:147], v[210:213], v[20:23]
	v_mfma_f32_16x16x32_bf16 v[12:15], v[158:161], v[210:213], v[12:15]
	v_mfma_f32_16x16x32_bf16 v[60:63], v[148:151], v[186:189], v[60:63]
	v_mfma_f32_16x16x32_bf16 v[56:59], v[162:165], v[186:189], v[56:59]
	v_mfma_f32_16x16x32_bf16 v[52:55], v[148:151], v[194:197], v[52:55]
	v_mfma_f32_16x16x32_bf16 v[44:47], v[162:165], v[194:197], v[44:47]
	v_mfma_f32_16x16x32_bf16 v[36:39], v[148:151], v[204:207], v[36:39]
	v_mfma_f32_16x16x32_bf16 v[28:31], v[162:165], v[204:207], v[28:31]
	v_mfma_f32_16x16x32_bf16 v[20:23], v[148:151], v[214:217], v[20:23]
	v_mfma_f32_16x16x32_bf16 v[12:15], v[162:165], v[214:217], v[12:15]
	s_setprio 0
	s_setprio 1
	v_mfma_f32_16x16x32_bf16 v[48:51], v[166:169], v[182:185], v[48:51]
	v_mfma_f32_16x16x32_bf16 v[40:43], v[174:177], v[182:185], v[40:43]
	v_mfma_f32_16x16x32_bf16 v[32:35], v[166:169], v[190:193], v[32:35]
	v_mfma_f32_16x16x32_bf16 v[24:27], v[174:177], v[190:193], v[24:27]
	v_mfma_f32_16x16x32_bf16 v[16:19], v[166:169], v[198:201], v[16:19]
	v_mfma_f32_16x16x32_bf16 v[8:11], v[174:177], v[198:201], v[8:11]
	v_mfma_f32_16x16x32_bf16 v[4:7], v[166:169], v[210:213], v[4:7]
	v_mfma_f32_16x16x32_bf16 v[0:3], v[174:177], v[210:213], v[0:3]
	v_mfma_f32_16x16x32_bf16 v[48:51], v[170:173], v[186:189], v[48:51]
	v_mfma_f32_16x16x32_bf16 v[40:43], v[178:181], v[186:189], v[40:43]
	v_mfma_f32_16x16x32_bf16 v[32:35], v[170:173], v[194:197], v[32:35]
	v_mfma_f32_16x16x32_bf16 v[24:27], v[178:181], v[194:197], v[24:27]
	v_mfma_f32_16x16x32_bf16 v[16:19], v[170:173], v[204:207], v[16:19]
	v_mfma_f32_16x16x32_bf16 v[8:11], v[178:181], v[204:207], v[8:11]
	v_mfma_f32_16x16x32_bf16 v[4:7], v[170:173], v[214:217], v[4:7]
	v_mfma_f32_16x16x32_bf16 v[0:3], v[178:181], v[214:217], v[0:3]
	s_setprio 0
	s_barrier
	s_add_u32 s46, s46, 0x100
	s_addc_u32 s47, s47, 0
	s_add_u32 s48, s48, 0x100
	s_addc_u32 s49, s49, 0
	s_cmp_ge_i32 s78, s64
	s_mov_b32 s10, s78
	s_cbranch_scc0 .LBB0_961
	v_and_b32_e32 v144, 3, v209
	v_bfe_u32 v145, v209, 4, 2
	v_and_or_b32 v146, v209, 12, v145
	v_lshl_or_b32 v147, v144, 4, v146
	v_lshlrev_b32_e32 v147, 2, v147
	v_and_or_b32 v148, v152, -16, v146
	v_and_b32_e32 v149, 0x60, v154
	v_lshl_or_b32 v149, v144, 3, v149
	v_max_f32_e32 v124, 0, v124
	v_max_f32_e32 v125, 0, v125
	v_max_f32_e32 v126, 0, v126
	v_max_f32_e32 v127, 0, v127
	v_max_f32_e32 v120, 0, v120
	v_max_f32_e32 v121, 0, v121
	v_max_f32_e32 v122, 0, v122
	v_max_f32_e32 v123, 0, v123
	v_pk_mul_f32 v[124:125], v[124:125], v[124:125]
	v_pk_mul_f32 v[126:127], v[126:127], v[126:127]
	v_pk_mul_f32 v[120:121], v[120:121], v[120:121]
	v_pk_mul_f32 v[122:123], v[122:123], v[122:123]
	v_cvt_pk_bf16_f32 v124, v124, v125
	v_cvt_pk_bf16_f32 v125, v126, v127
	v_cvt_pk_bf16_f32 v126, v120, v121
	v_cvt_pk_bf16_f32 v127, v122, v123
	ds_bpermute_b32 v124, v147, v124
	ds_bpermute_b32 v125, v147, v125
	ds_bpermute_b32 v126, v147, v126
	ds_bpermute_b32 v127, v147, v127
	v_max_f32_e32 v116, 0, v116
	v_max_f32_e32 v117, 0, v117
	v_max_f32_e32 v118, 0, v118
	v_max_f32_e32 v119, 0, v119
	v_max_f32_e32 v108, 0, v108
	v_max_f32_e32 v109, 0, v109
	v_max_f32_e32 v110, 0, v110
	v_max_f32_e32 v111, 0, v111
	v_pk_mul_f32 v[116:117], v[116:117], v[116:117]
	v_pk_mul_f32 v[118:119], v[118:119], v[118:119]
	v_pk_mul_f32 v[108:109], v[108:109], v[108:109]
	v_pk_mul_f32 v[110:111], v[110:111], v[110:111]
	v_cvt_pk_bf16_f32 v116, v116, v117
	v_cvt_pk_bf16_f32 v117, v118, v119
	v_cvt_pk_bf16_f32 v118, v108, v109
	v_cvt_pk_bf16_f32 v119, v110, v111
	ds_bpermute_b32 v116, v147, v116
	ds_bpermute_b32 v117, v147, v117
	ds_bpermute_b32 v118, v147, v118
	ds_bpermute_b32 v119, v147, v119
	v_max_f32_e32 v100, 0, v100
	v_max_f32_e32 v101, 0, v101
	v_max_f32_e32 v102, 0, v102
	v_max_f32_e32 v103, 0, v103
	v_max_f32_e32 v92, 0, v92
	v_max_f32_e32 v93, 0, v93
	v_max_f32_e32 v94, 0, v94
	v_max_f32_e32 v95, 0, v95
	v_pk_mul_f32 v[100:101], v[100:101], v[100:101]
	v_pk_mul_f32 v[102:103], v[102:103], v[102:103]
	v_pk_mul_f32 v[92:93], v[92:93], v[92:93]
	v_pk_mul_f32 v[94:95], v[94:95], v[94:95]
	v_cvt_pk_bf16_f32 v100, v100, v101
	v_cvt_pk_bf16_f32 v101, v102, v103
	v_cvt_pk_bf16_f32 v102, v92, v93
	v_cvt_pk_bf16_f32 v103, v94, v95
	ds_bpermute_b32 v100, v147, v100
	ds_bpermute_b32 v101, v147, v101
	ds_bpermute_b32 v102, v147, v102
	ds_bpermute_b32 v103, v147, v103
	v_max_f32_e32 v84, 0, v84
	v_max_f32_e32 v85, 0, v85
	v_max_f32_e32 v86, 0, v86
	v_max_f32_e32 v87, 0, v87
	v_max_f32_e32 v76, 0, v76
	v_max_f32_e32 v77, 0, v77
	v_max_f32_e32 v78, 0, v78
	v_max_f32_e32 v79, 0, v79
	v_pk_mul_f32 v[84:85], v[84:85], v[84:85]
	v_pk_mul_f32 v[86:87], v[86:87], v[86:87]
	v_pk_mul_f32 v[76:77], v[76:77], v[76:77]
	v_pk_mul_f32 v[78:79], v[78:79], v[78:79]
	v_cvt_pk_bf16_f32 v84, v84, v85
	v_cvt_pk_bf16_f32 v85, v86, v87
	v_cvt_pk_bf16_f32 v86, v76, v77
	v_cvt_pk_bf16_f32 v87, v78, v79
	ds_bpermute_b32 v84, v147, v84
	ds_bpermute_b32 v85, v147, v85
	ds_bpermute_b32 v86, v147, v86
	ds_bpermute_b32 v87, v147, v87
	v_max_f32_e32 v112, 0, v112
	v_max_f32_e32 v113, 0, v113
	v_max_f32_e32 v114, 0, v114
	v_max_f32_e32 v115, 0, v115
	v_max_f32_e32 v104, 0, v104
	v_max_f32_e32 v105, 0, v105
	v_max_f32_e32 v106, 0, v106
	v_max_f32_e32 v107, 0, v107
	v_pk_mul_f32 v[112:113], v[112:113], v[112:113]
	v_pk_mul_f32 v[114:115], v[114:115], v[114:115]
	v_pk_mul_f32 v[104:105], v[104:105], v[104:105]
	v_pk_mul_f32 v[106:107], v[106:107], v[106:107]
	v_cvt_pk_bf16_f32 v112, v112, v113
	v_cvt_pk_bf16_f32 v113, v114, v115
	v_cvt_pk_bf16_f32 v114, v104, v105
	v_cvt_pk_bf16_f32 v115, v106, v107
	ds_bpermute_b32 v112, v147, v112
	ds_bpermute_b32 v113, v147, v113
	ds_bpermute_b32 v114, v147, v114
	ds_bpermute_b32 v115, v147, v115
	v_max_f32_e32 v96, 0, v96
	v_max_f32_e32 v97, 0, v97
	v_max_f32_e32 v98, 0, v98
	v_max_f32_e32 v99, 0, v99
	v_max_f32_e32 v88, 0, v88
	v_max_f32_e32 v89, 0, v89
	v_max_f32_e32 v90, 0, v90
	v_max_f32_e32 v91, 0, v91
	v_pk_mul_f32 v[96:97], v[96:97], v[96:97]
	v_pk_mul_f32 v[98:99], v[98:99], v[98:99]
	v_pk_mul_f32 v[88:89], v[88:89], v[88:89]
	v_pk_mul_f32 v[90:91], v[90:91], v[90:91]
	v_cvt_pk_bf16_f32 v96, v96, v97
	v_cvt_pk_bf16_f32 v97, v98, v99
	v_cvt_pk_bf16_f32 v98, v88, v89
	v_cvt_pk_bf16_f32 v99, v90, v91
	ds_bpermute_b32 v96, v147, v96
	ds_bpermute_b32 v97, v147, v97
	ds_bpermute_b32 v98, v147, v98
	ds_bpermute_b32 v99, v147, v99
	v_max_f32_e32 v80, 0, v80
	v_max_f32_e32 v81, 0, v81
	v_max_f32_e32 v82, 0, v82
	v_max_f32_e32 v83, 0, v83
	v_max_f32_e32 v72, 0, v72
	v_max_f32_e32 v73, 0, v73
	v_max_f32_e32 v74, 0, v74
	v_max_f32_e32 v75, 0, v75
	v_pk_mul_f32 v[80:81], v[80:81], v[80:81]
	v_pk_mul_f32 v[82:83], v[82:83], v[82:83]
	v_pk_mul_f32 v[72:73], v[72:73], v[72:73]
	v_pk_mul_f32 v[74:75], v[74:75], v[74:75]
	v_cvt_pk_bf16_f32 v80, v80, v81
	v_cvt_pk_bf16_f32 v81, v82, v83
	v_cvt_pk_bf16_f32 v82, v72, v73
	v_cvt_pk_bf16_f32 v83, v74, v75
	ds_bpermute_b32 v80, v147, v80
	ds_bpermute_b32 v81, v147, v81
	ds_bpermute_b32 v82, v147, v82
	ds_bpermute_b32 v83, v147, v83
	v_max_f32_e32 v68, 0, v68
	v_max_f32_e32 v69, 0, v69
	v_max_f32_e32 v70, 0, v70
	v_max_f32_e32 v71, 0, v71
	v_max_f32_e32 v64, 0, v64
	v_max_f32_e32 v65, 0, v65
	v_max_f32_e32 v66, 0, v66
	v_max_f32_e32 v67, 0, v67
	v_pk_mul_f32 v[68:69], v[68:69], v[68:69]
	v_pk_mul_f32 v[70:71], v[70:71], v[70:71]
	v_pk_mul_f32 v[64:65], v[64:65], v[64:65]
	v_pk_mul_f32 v[66:67], v[66:67], v[66:67]
	v_cvt_pk_bf16_f32 v68, v68, v69
	v_cvt_pk_bf16_f32 v69, v70, v71
	v_cvt_pk_bf16_f32 v70, v64, v65
	v_cvt_pk_bf16_f32 v71, v66, v67
	ds_bpermute_b32 v68, v147, v68
	ds_bpermute_b32 v69, v147, v69
	ds_bpermute_b32 v70, v147, v70
	ds_bpermute_b32 v71, v147, v71
	v_max_f32_e32 v60, 0, v60
	v_max_f32_e32 v61, 0, v61
	v_max_f32_e32 v62, 0, v62
	v_max_f32_e32 v63, 0, v63
	v_max_f32_e32 v56, 0, v56
	v_max_f32_e32 v57, 0, v57
	v_max_f32_e32 v58, 0, v58
	v_max_f32_e32 v59, 0, v59
	v_pk_mul_f32 v[60:61], v[60:61], v[60:61]
	v_pk_mul_f32 v[62:63], v[62:63], v[62:63]
	v_pk_mul_f32 v[56:57], v[56:57], v[56:57]
	v_pk_mul_f32 v[58:59], v[58:59], v[58:59]
	v_cvt_pk_bf16_f32 v60, v60, v61
	v_cvt_pk_bf16_f32 v61, v62, v63
	v_cvt_pk_bf16_f32 v62, v56, v57
	v_cvt_pk_bf16_f32 v63, v58, v59
	ds_bpermute_b32 v60, v147, v60
	ds_bpermute_b32 v61, v147, v61
	ds_bpermute_b32 v62, v147, v62
	ds_bpermute_b32 v63, v147, v63
	v_max_f32_e32 v52, 0, v52
	v_max_f32_e32 v53, 0, v53
	v_max_f32_e32 v54, 0, v54
	v_max_f32_e32 v55, 0, v55
	v_max_f32_e32 v44, 0, v44
	v_max_f32_e32 v45, 0, v45
	v_max_f32_e32 v46, 0, v46
	v_max_f32_e32 v47, 0, v47
	v_pk_mul_f32 v[52:53], v[52:53], v[52:53]
	v_pk_mul_f32 v[54:55], v[54:55], v[54:55]
	v_pk_mul_f32 v[44:45], v[44:45], v[44:45]
	v_pk_mul_f32 v[46:47], v[46:47], v[46:47]
	v_cvt_pk_bf16_f32 v52, v52, v53
	v_cvt_pk_bf16_f32 v53, v54, v55
	v_cvt_pk_bf16_f32 v54, v44, v45
	v_cvt_pk_bf16_f32 v55, v46, v47
	ds_bpermute_b32 v52, v147, v52
	ds_bpermute_b32 v53, v147, v53
	ds_bpermute_b32 v54, v147, v54
	ds_bpermute_b32 v55, v147, v55
	v_max_f32_e32 v36, 0, v36
	v_max_f32_e32 v37, 0, v37
	v_max_f32_e32 v38, 0, v38
	v_max_f32_e32 v39, 0, v39
	v_max_f32_e32 v28, 0, v28
	v_max_f32_e32 v29, 0, v29
	v_max_f32_e32 v30, 0, v30
	v_max_f32_e32 v31, 0, v31
	v_pk_mul_f32 v[36:37], v[36:37], v[36:37]
	v_pk_mul_f32 v[38:39], v[38:39], v[38:39]
	v_pk_mul_f32 v[28:29], v[28:29], v[28:29]
	v_pk_mul_f32 v[30:31], v[30:31], v[30:31]
	v_cvt_pk_bf16_f32 v36, v36, v37
	v_cvt_pk_bf16_f32 v37, v38, v39
	v_cvt_pk_bf16_f32 v38, v28, v29
	v_cvt_pk_bf16_f32 v39, v30, v31
	ds_bpermute_b32 v36, v147, v36
	ds_bpermute_b32 v37, v147, v37
	ds_bpermute_b32 v38, v147, v38
	ds_bpermute_b32 v39, v147, v39
	v_max_f32_e32 v20, 0, v20
	v_max_f32_e32 v21, 0, v21
	v_max_f32_e32 v22, 0, v22
	v_max_f32_e32 v23, 0, v23
	v_max_f32_e32 v12, 0, v12
	v_max_f32_e32 v13, 0, v13
	v_max_f32_e32 v14, 0, v14
	v_max_f32_e32 v15, 0, v15
	v_pk_mul_f32 v[20:21], v[20:21], v[20:21]
	v_pk_mul_f32 v[22:23], v[22:23], v[22:23]
	v_pk_mul_f32 v[12:13], v[12:13], v[12:13]
	v_pk_mul_f32 v[14:15], v[14:15], v[14:15]
	v_cvt_pk_bf16_f32 v20, v20, v21
	v_cvt_pk_bf16_f32 v21, v22, v23
	v_cvt_pk_bf16_f32 v22, v12, v13
	v_cvt_pk_bf16_f32 v23, v14, v15
	ds_bpermute_b32 v20, v147, v20
	ds_bpermute_b32 v21, v147, v21
	ds_bpermute_b32 v22, v147, v22
	ds_bpermute_b32 v23, v147, v23
	v_max_f32_e32 v48, 0, v48
	v_max_f32_e32 v49, 0, v49
	v_max_f32_e32 v50, 0, v50
	v_max_f32_e32 v51, 0, v51
	v_max_f32_e32 v40, 0, v40
	v_max_f32_e32 v41, 0, v41
	v_max_f32_e32 v42, 0, v42
	v_max_f32_e32 v43, 0, v43
	v_pk_mul_f32 v[48:49], v[48:49], v[48:49]
	v_pk_mul_f32 v[50:51], v[50:51], v[50:51]
	v_pk_mul_f32 v[40:41], v[40:41], v[40:41]
	v_pk_mul_f32 v[42:43], v[42:43], v[42:43]
	v_cvt_pk_bf16_f32 v48, v48, v49
	v_cvt_pk_bf16_f32 v49, v50, v51
	v_cvt_pk_bf16_f32 v50, v40, v41
	v_cvt_pk_bf16_f32 v51, v42, v43
	ds_bpermute_b32 v48, v147, v48
	ds_bpermute_b32 v49, v147, v49
	ds_bpermute_b32 v50, v147, v50
	ds_bpermute_b32 v51, v147, v51
	v_max_f32_e32 v32, 0, v32
	v_max_f32_e32 v33, 0, v33
	v_max_f32_e32 v34, 0, v34
	v_max_f32_e32 v35, 0, v35
	v_max_f32_e32 v24, 0, v24
	v_max_f32_e32 v25, 0, v25
	v_max_f32_e32 v26, 0, v26
	v_max_f32_e32 v27, 0, v27
	v_pk_mul_f32 v[32:33], v[32:33], v[32:33]
	v_pk_mul_f32 v[34:35], v[34:35], v[34:35]
	v_pk_mul_f32 v[24:25], v[24:25], v[24:25]
	v_pk_mul_f32 v[26:27], v[26:27], v[26:27]
	v_cvt_pk_bf16_f32 v32, v32, v33
	v_cvt_pk_bf16_f32 v33, v34, v35
	v_cvt_pk_bf16_f32 v34, v24, v25
	v_cvt_pk_bf16_f32 v35, v26, v27
	ds_bpermute_b32 v32, v147, v32
	ds_bpermute_b32 v33, v147, v33
	ds_bpermute_b32 v34, v147, v34
	ds_bpermute_b32 v35, v147, v35
	v_max_f32_e32 v16, 0, v16
	v_max_f32_e32 v17, 0, v17
	v_max_f32_e32 v18, 0, v18
	v_max_f32_e32 v19, 0, v19
	v_max_f32_e32 v8, 0, v8
	v_max_f32_e32 v9, 0, v9
	v_max_f32_e32 v10, 0, v10
	v_max_f32_e32 v11, 0, v11
	v_pk_mul_f32 v[16:17], v[16:17], v[16:17]
	v_pk_mul_f32 v[18:19], v[18:19], v[18:19]
	v_pk_mul_f32 v[8:9], v[8:9], v[8:9]
	v_pk_mul_f32 v[10:11], v[10:11], v[10:11]
	v_cvt_pk_bf16_f32 v16, v16, v17
	v_cvt_pk_bf16_f32 v17, v18, v19
	v_cvt_pk_bf16_f32 v18, v8, v9
	v_cvt_pk_bf16_f32 v19, v10, v11
	ds_bpermute_b32 v16, v147, v16
	ds_bpermute_b32 v17, v147, v17
	ds_bpermute_b32 v18, v147, v18
	ds_bpermute_b32 v19, v147, v19
	v_max_f32_e32 v4, 0, v4
	v_max_f32_e32 v5, 0, v5
	v_max_f32_e32 v6, 0, v6
	v_max_f32_e32 v7, 0, v7
	v_max_f32_e32 v0, 0, v0
	v_max_f32_e32 v1, 0, v1
	v_max_f32_e32 v2, 0, v2
	v_max_f32_e32 v3, 0, v3
	v_pk_mul_f32 v[4:5], v[4:5], v[4:5]
	v_pk_mul_f32 v[6:7], v[6:7], v[6:7]
	v_pk_mul_f32 v[0:1], v[0:1], v[0:1]
	v_pk_mul_f32 v[2:3], v[2:3], v[2:3]
	v_cvt_pk_bf16_f32 v4, v4, v5
	v_cvt_pk_bf16_f32 v5, v6, v7
	v_cvt_pk_bf16_f32 v6, v0, v1
	v_cvt_pk_bf16_f32 v7, v2, v3
	ds_bpermute_b32 v4, v147, v4
	ds_bpermute_b32 v5, v147, v5
	ds_bpermute_b32 v6, v147, v6
	ds_bpermute_b32 v7, v147, v7

.LBB0_965:
	s_mov_b64 vcc, 0x20000
	v_lshl_add_u32 v148, s76, 8, v148
	v_lshl_or_b32 v149, s77, 8, v149
	v_lshlrev_b32_e32 v148, 13, v148
	v_lshl_add_u32 v150, v149, 1, v148
	v_mov_b32_e32 v151, 0
	v_lshl_add_u64 v[120:121], s[30:31], 0, v[150:151]
	v_lshl_add_u64 v[108:109], v[120:121], 0, vcc
	v_lshl_add_u64 v[92:93], v[108:109], 0, vcc
	v_lshl_add_u64 v[76:77], v[92:93], 0, vcc
	v_lshl_add_u64 v[56:57], v[120:121], 0, s[36:37]
	v_lshl_add_u64 v[44:45], v[108:109], 0, s[36:37]
	v_lshl_add_u64 v[28:29], v[92:93], 0, s[36:37]
	v_lshl_add_u64 v[12:13], v[76:77], 0, s[36:37]
	s_waitcnt lgkmcnt(0)
	global_store_dwordx4 v[120:121], v[124:127], off nt
	global_store_dwordx4 v[120:121], v[112:115], off offset:256 nt
	global_store_dwordx4 v[108:109], v[116:119], off nt
	global_store_dwordx4 v[108:109], v[96:99], off offset:256 nt
	global_store_dwordx4 v[92:93], v[100:103], off nt
	global_store_dwordx4 v[92:93], v[80:83], off offset:256 nt
	global_store_dwordx4 v[76:77], v[84:87], off nt
	global_store_dwordx4 v[76:77], v[68:71], off offset:256 nt
	global_store_dwordx4 v[56:57], v[60:63], off nt
	global_store_dwordx4 v[56:57], v[48:51], off offset:256 nt
	global_store_dwordx4 v[44:45], v[52:55], off nt
	global_store_dwordx4 v[44:45], v[32:35], off offset:256 nt
	global_store_dwordx4 v[28:29], v[36:39], off nt
	global_store_dwordx4 v[28:29], v[16:19], off offset:256 nt
	global_store_dwordx4 v[12:13], v[20:23], off nt
	global_store_dwordx4 v[12:13], v[4:7], off offset:256 nt
	s_and_b64 vcc, exec, s[0:1]
	s_mov_b64 s[0:1], -1
	s_cbranch_vccnz .LBB0_948
	s_andn2_b64 vcc, exec, s[20:21]
	s_cbranch_vccnz .LBB0_947
	s_barrier
	s_branch .LBB0_947
